# speedup vs baseline: 1.0039x; 1.0010x over previous
; DI unsigned cvtpk(float lo, float hi) { f32x2_t v = {lo, hi}; bf16x2_t b = __builtin_convertvector(v, bf16x2_t); return __builtin_bit_cast(unsigned, b); }
; #define PHASE_BEGIN KArg pp = kargs(); unsigned char* ws = pp->ws; int ll = l; asm volatile("" : "+s"(ll)); (void)ws; (void)ll;
; __global__ void __launch_bounds__(NTHR, 2) mega_fwd(Params P) {
;     ...
;             PHASE_BEGIN THREAD_IDS
;             const float* gq = pp->in[8] + (size_t)ll * 384; const float* gkv = pp->in[10] + (size_t)ll * 256;
;             const float* T1 = B_T1; bf16_t* CKVB = B_CKVB; bf16_t* KR = B_KR; bf16_t* CQ = B_CQ; float* GLR = B_GLR; const float2* tabM = B_TABM;
;             float* outp = pp->out;
;             for (int m0 = gw; m0 < MT; m0 += 2 * NGW) {
;                 const int m1 = m0 + NGW; const bool has1 = m1 < MT; const int mm[2] = {m0, has1 ? m1 : m0};
;                 f32x4 vk[2], vq0[2], vq1[2]; float x1[2], x2[2], gl[2];
; #pragma unroll
;                 for (int k = 0; k < 2; ++k) {
;                     const float* t = T1 + (size_t)mm[k] * NIN_MLA;
;                     vk[k] = ((const f32x4*)t)[lane];
;                     vq0[k] = ((const f32x4*)(t + 256))[lane];
;                     vq1[k] = (f32x4){0.f, 0.f, 0.f, 0.f}; if (lane < 32) vq1[k] = ((const f32x4*)(t + 512))[lane];
;                     x1[k] = 0.f; x2[k] = 0.f; gl[k] = 0.f;
;                     if (lane < 16) { x1[k] = t[640 + lane]; x2[k] = t[656 + lane]; } else if (lane < 32) gl[k] = t[672 + (lane - 16)];
;     ...
;                         const f32x4 o = vk[k] * rs * ((const f32x4*)gkv)[lane];
;                         ((f32x4*)ockv)[lane] = o;
;                         u32x2 w; w.x = cvtpk(o.x, o.y); w.y = cvtpk(o.z, o.w); ((u32x2*)(CKVB + kvr * 256))[lane] = w;
;                     }
;                     {
;                         const float rs = 1.f / sqrtf(sq[k] * (1.f / 384.f) + EPS);
;                         const f32x4 o0 = vq0[k] * rs * ((const f32x4*)gq)[lane];
;                         u32x2 w; w.x = cvtpk(o0.x, o0.y); w.y = cvtpk(o0.z, o0.w); ((u32x2*)(CQ + (size_t)m * 384))[lane] = w;
;                         if (lane < 32) { const f32x4 o1 = vq1[k] * rs * ((const f32x4*)(gq + 256))[lane]; u32x2 w1; w1.x = cvtpk(o1.x, o1.y); w1.y = cvtpk(o1.z, o1.w); ((u32x2*)(CQ + (size_t)m * 384 + 256))[lane] = w1; }
.LBB0_528:
	s_or_b64 exec, exec, s[34:35]
	v_readlane_b32 s4, v247, 50
	s_mov_b64 s[40:41], s[90:91]
	s_mov_b32 s44, s4
	v_mov_b32_e32 v1, v212
	s_mov_b32 s4, s2
	s_waitcnt lgkmcnt(0)
	s_barrier
	s_nop 0
	v_ashrrev_i32_e32 v2, 6, v1
	v_lshl_add_u32 v26, s4, 3, v2
	s_mov_b32 s4, 0x8200
	v_cmp_gt_i32_e32 vcc, s4, v26
	s_and_saveexec_b64 s[34:35], vcc
	s_cbranch_execz .LBB0_576
	s_load_dwordx4 s[52:55], s[40:41], 0xc8
	s_load_dwordx2 s[4:5], s[40:41], 0x40
	s_load_dwordx2 s[6:7], s[40:41], 0x50
	v_and_b32_e32 v28, 63, v1
	v_and_b32_e32 v1, 64, v220
	v_lshlrev_b32_e32 v2, 4, v28
	s_waitcnt lgkmcnt(0)
	s_add_u32 s50, s54, 0x10400000
	s_addc_u32 s51, s55, 0
	s_add_u32 s56, s54, 0x7d00000
	s_addc_u32 s57, s55, 0
	s_ashr_i32 s45, s44, 31
	s_lshl_b64 s[8:9], s[44:45], 10
	s_add_u32 s6, s6, s8
	s_addc_u32 s7, s7, s9
	s_mul_i32 s9, s44, 0x600
	s_mul_hi_i32 s8, s44, 0x600
	s_add_u32 s4, s4, s9
	s_addc_u32 s5, s5, s8
	v_mov_b32_e32 v3, v0
	v_add_u32_e32 v1, 64, v1
	v_lshl_add_u64 v[30:31], s[6:7], 0, v[2:3]
	v_lshl_add_u64 v[36:37], s[4:5], 0, v[2:3]
	global_load_dwordx4 v[100:103], v[30:31], off
	global_load_dwordx4 v[104:107], v[36:37], off
	v_bfe_i32 v115, v220, 5, 1
	v_lshlrev_b32_e32 v114, 9, v115
	v_lshl_add_u64 v[112:113], v[36:37], 0, v[114:115]
	global_load_dwordx4 v[108:111], v[112:113], off offset:1024
	v_xor_b32_e32 v3, 1, v220
	v_cmp_lt_i32_e32 vcc, v3, v1
	v_lshlrev_b32_e32 v8, 1, v28
	v_mov_b32_e32 v9, v0
	v_cndmask_b32_e32 v3, v220, v3, vcc
	v_lshlrev_b32_e32 v29, 2, v3
	v_xor_b32_e32 v3, 2, v220
	v_cmp_lt_i32_e32 vcc, v3, v1
	v_lshlrev_b32_e32 v32, 3, v28
	v_mov_b32_e32 v33, v0
	v_cndmask_b32_e32 v3, v220, v3, vcc
	v_lshlrev_b32_e32 v76, 2, v3
	v_xor_b32_e32 v3, 4, v220
	v_cmp_lt_i32_e32 vcc, v3, v1
	v_lshl_add_u64 v[8:9], s[54:55], 0, v[8:9]
	s_mov_b64 s[4:5], 0x1c000000
	v_cndmask_b32_e32 v3, v220, v3, vcc
	v_lshlrev_b32_e32 v77, 2, v3
	v_xor_b32_e32 v3, 8, v220
	v_cmp_lt_i32_e32 vcc, v3, v1
	v_lshl_add_u64 v[4:5], s[54:55], 0, v[32:33]
	v_lshl_add_u64 v[40:41], v[8:9], 0, s[4:5]
	v_cndmask_b32_e32 v3, v220, v3, vcc
	s_mov_b64 s[4:5], 0x18600000
	s_mov_b64 s[6:7], 0x19f00000
	v_lshlrev_b32_e32 v78, 2, v3
	v_xor_b32_e32 v3, 16, v220
	v_lshl_add_u64 v[44:45], v[4:5], 0, s[4:5]
	v_ashrrev_i32_e32 v27, 31, v26
	s_movk_i32 s4, 0x300
	v_lshl_add_u64 v[34:35], v[4:5], 0, s[6:7]
	v_lshlrev_b32_e32 v6, 2, v28
	v_mov_b32_e32 v7, v0
	v_cmp_lt_i32_e32 vcc, v3, v1
	v_mad_i64_i32 v[46:47], s[4:5], v26, s4, v[32:33]
	v_lshlrev_b64 v[4:5], 6, v[26:27]
	v_cndmask_b32_e32 v3, v220, v3, vcc
	v_lshl_add_u64 v[4:5], v[4:5], 0, v[6:7]
	s_mov_b64 s[4:5], 0x7dfffc0
	v_lshlrev_b32_e32 v79, 2, v3
	v_xor_b32_e32 v3, 32, v220
	v_lshl_add_u64 v[48:49], v[4:5], 0, s[4:5]
	s_movk_i32 s4, 0xc00
	v_cmp_lt_i32_e32 vcc, v3, v1
	v_mad_i64_i32 v[4:5], s[4:5], v26, s4, 0
	s_nop 0
	v_cndmask_b32_e32 v1, v220, v3, vcc
	v_mul_hi_i32_i24_e32 v43, -12, v28
	v_mul_i32_i24_e32 v42, -12, v28
	v_or_b32_e32 v50, v4, v2
	v_mov_b32_e32 v51, v5
	v_or_b32_e32 v4, v4, v6
	s_mov_b64 s[4:5], 0x10400a40
	s_movk_i32 s9, 0x7fff
	v_cmp_gt_u32_e64 s[40:41], 32, v28
	v_cmp_lt_u32_e64 s[42:43], 15, v28
	s_lshl_b64 s[58:59], s[44:45], 9
	s_lshl_b64 s[60:61], s[44:45], 15
	v_lshl_add_u64 v[38:39], s[54:55], 0, v[6:7]
	v_lshlrev_b32_e32 v80, 2, v1
	v_lshl_add_u64 v[52:53], v[50:51], 0, v[42:43]
	v_lshl_add_u64 v[54:55], v[4:5], 0, s[4:5]
	s_mov_b64 s[62:63], 0
	s_branch .LBB0_531

; DI unsigned cvtpk(float lo, float hi) { f32x2_t v = {lo, hi}; bf16x2_t b = __builtin_convertvector(v, bf16x2_t); return __builtin_bit_cast(unsigned, b); }
; __global__ void __launch_bounds__(NTHR, 2) mega_fwd(Params P) {
;     ...
;                 float sk[2], sq[2];
; #pragma unroll
;                 for (int k = 0; k < 2; ++k) {
;                     sk[k] = (vk[k].x * vk[k].x + vk[k].y * vk[k].y) + (vk[k].z * vk[k].z + vk[k].w * vk[k].w);
;                     sq[k] = (vq0[k].x * vq0[k].x + vq0[k].y * vq0[k].y) + (vq0[k].z * vq0[k].z + vq0[k].w * vq0[k].w) + (vq1[k].x * vq1[k].x + vq1[k].y * vq1[k].y) + (vq1[k].z * vq1[k].z + vq1[k].w * vq1[k].w);
;                 }
; #pragma unroll
;                 for (int o = 1; o < 64; o <<= 1)
; #pragma unroll
;                     for (int k = 0; k < 2; ++k) { sk[k] += __shfl_xor(sk[k], o); sq[k] += __shfl_xor(sq[k], o); }
; #pragma unroll
;                 for (int k = 0; k < 2; ++k) {
;                     if (k == 1 && !has1) break;
;                     const int m = mm[k]; const int pos = pos_of_row(m); const size_t kvr = (size_t)kvrow_of_row(m);
;                     float* ockv; float* okr;
;                     if (m < MP) { ockv = outp + O_CKVP + ((size_t)ll * MP + m) * 256; okr = outp + O_KRP + ((size_t)ll * MP + m) * 32; }
;                     else { ockv = outp + O_CKVS + ((size_t)ll * MS + (m - MP)) * 256; okr = outp + O_KRS + ((size_t)ll * MS + (m - MP)) * 32; }
;                     {
;                         const float rs = 1.f / sqrtf(sk[k] * (1.f / 256.f) + EPS);
;                         const f32x4 o = vk[k] * rs * ((const f32x4*)gkv)[lane];
;                         ((f32x4*)ockv)[lane] = o;
;                         u32x2 w; w.x = cvtpk(o.x, o.y); w.y = cvtpk(o.z, o.w); ((u32x2*)(CKVB + kvr * 256))[lane] = w;
;                     }
;                     {
;                         const float rs = 1.f / sqrtf(sq[k] * (1.f / 384.f) + EPS);
;                         const f32x4 o0 = vq0[k] * rs * ((const f32x4*)gq)[lane];
;                         u32x2 w; w.x = cvtpk(o0.x, o0.y); w.y = cvtpk(o0.z, o0.w); ((u32x2*)(CQ + (size_t)m * 384))[lane] = w;
;                         if (lane < 32) { const f32x4 o1 = vq1[k] * rs * ((const f32x4*)(gq + 256))[lane]; u32x2 w1; w1.x = cvtpk(o1.x, o1.y); w1.y = cvtpk(o1.z, o1.w); ((u32x2*)(CQ + (size_t)m * 384 + 256))[lane] = w1; }
;                     }
.LBB0_547:
	s_or_b64 exec, exec, s[46:47]
	s_waitcnt vmcnt(3)
	v_mul_f32_e32 v33, v23, v23
	v_mul_f32_e32 v57, v25, v25
	v_fmac_f32_e32 v33, v22, v22
	v_fmac_f32_e32 v57, v24, v24
	v_add_f32_e32 v33, v33, v57
	s_waitcnt vmcnt(2)
	v_mul_f32_e32 v57, v19, v19
	v_mul_f32_e32 v59, v21, v21
	v_fmac_f32_e32 v57, v18, v18
	v_fmac_f32_e32 v59, v20, v20
	v_add_f32_e32 v57, v57, v59
	v_mul_f32_e32 v59, v15, v15
	v_fmac_f32_e32 v59, v14, v14
	v_add_f32_e32 v57, v59, v57
	v_mul_f32_e32 v59, v17, v17
	v_fmac_f32_e32 v59, v16, v16
	v_add_f32_e32 v57, v59, v57
	s_waitcnt vmcnt(1)
	v_mul_f32_e32 v59, v11, v11
	v_mul_f32_e32 v65, v13, v13
	v_fmac_f32_e32 v59, v10, v10
	v_fmac_f32_e32 v65, v12, v12
	v_add_f32_e32 v59, v59, v65
	s_waitcnt vmcnt(0)
	v_mul_f32_e32 v65, v7, v7
	s_waitcnt lgkmcnt(1)
	v_mul_f32_e32 v67, v9, v9
	v_fmac_f32_e32 v65, v6, v6
	v_fmac_f32_e32 v67, v8, v8
	v_add_f32_e32 v65, v65, v67
	v_mul_f32_e32 v67, v3, v3
	v_fmac_f32_e32 v67, v2, v2
	v_add_f32_e32 v65, v67, v65
	v_mul_f32_e32 v67, v5, v5
	v_fmac_f32_e32 v67, v4, v4
	v_add_f32_e32 v65, v67, v65
	ds_bpermute_b32 v67, v29, v33
	ds_bpermute_b32 v68, v29, v57
	ds_bpermute_b32 v69, v29, v59
	ds_bpermute_b32 v70, v29, v65
	s_mov_b32 s4, 0x8000
	s_waitcnt lgkmcnt(3)
	v_add_f32_e32 v33, v33, v67
	s_waitcnt lgkmcnt(2)
	v_add_f32_e32 v57, v57, v68
	s_waitcnt lgkmcnt(1)
	v_add_f32_e32 v59, v59, v69
	s_waitcnt lgkmcnt(0)
	v_add_f32_e32 v65, v65, v70
	ds_bpermute_b32 v67, v76, v33
	ds_bpermute_b32 v68, v76, v57
	ds_bpermute_b32 v69, v76, v59
	ds_bpermute_b32 v70, v76, v65
	v_cmp_gt_i32_e64 s[46:47], s4, v26
	s_waitcnt lgkmcnt(3)
	v_add_f32_e32 v33, v33, v67
	s_waitcnt lgkmcnt(2)
	v_add_f32_e32 v57, v57, v68
	s_waitcnt lgkmcnt(1)
	v_add_f32_e32 v59, v59, v69
	s_waitcnt lgkmcnt(0)
	v_add_f32_e32 v65, v65, v70
	ds_bpermute_b32 v67, v77, v33
	ds_bpermute_b32 v68, v77, v57
	ds_bpermute_b32 v69, v77, v59
	ds_bpermute_b32 v70, v77, v65
	v_cmp_lt_i32_e32 vcc, s9, v26
	s_waitcnt lgkmcnt(3)
	v_add_f32_e32 v33, v33, v67
	s_waitcnt lgkmcnt(2)
	v_add_f32_e32 v57, v57, v68
	s_waitcnt lgkmcnt(1)
	v_add_f32_e32 v59, v59, v69
	s_waitcnt lgkmcnt(0)
	v_add_f32_e32 v65, v65, v70
	ds_bpermute_b32 v67, v78, v33
	ds_bpermute_b32 v68, v78, v57
	ds_bpermute_b32 v69, v78, v59
	ds_bpermute_b32 v70, v78, v65
	v_add_u32_e32 v72, 0xffff8000, v26
	s_waitcnt lgkmcnt(3)
	v_add_f32_e32 v33, v33, v67
	s_waitcnt lgkmcnt(2)
	v_add_f32_e32 v57, v57, v68
	s_waitcnt lgkmcnt(1)
	v_add_f32_e32 v59, v59, v69
	s_waitcnt lgkmcnt(0)
	v_add_f32_e32 v67, v65, v70
	ds_bpermute_b32 v65, v79, v33
	ds_bpermute_b32 v68, v79, v57
	ds_bpermute_b32 v69, v79, v59
	ds_bpermute_b32 v70, v79, v67
	s_waitcnt lgkmcnt(3)
	v_add_f32_e32 v65, v33, v65
	s_waitcnt lgkmcnt(2)
	v_add_f32_e32 v82, v57, v68
	s_waitcnt lgkmcnt(1)
	v_add_f32_e32 v33, v59, v69
	s_waitcnt lgkmcnt(0)
	v_add_f32_e32 v57, v67, v70
	ds_bpermute_b32 v83, v80, v65
	ds_bpermute_b32 v84, v80, v82
	ds_bpermute_b32 v67, v80, v33
	ds_bpermute_b32 v81, v80, v57
	v_and_b32_e32 v59, 63, v26
	v_mov_b64_e32 v[68:69], v[26:27]
	s_and_saveexec_b64 s[48:49], vcc
	v_lshrrev_b32_e32 v68, 6, v72
	s_movk_i32 s4, 0x1040
	v_mul_lo_u32 v68, v68, s4
	v_or_b32_e32 v68, v68, v59
	v_add_u32_e32 v68, 0x9000, v68
	v_mov_b32_e32 v69, v0
	s_or_b64 exec, exec, s[48:49]
	s_and_saveexec_b64 s[4:5], vcc
	s_xor_b64 s[48:49], exec, s[4:5]
	v_mov_b32_e32 v73, v0
	v_lshl_add_u64 v[70:71], s[58:59], 0, v[72:73]
	s_or_saveexec_b64 s[48:49], s[48:49]
	v_mov_b64_e32 v[72:73], 0xd000000
	v_mov_b64_e32 v[74:75], 0xcf00000
	s_xor_b64 exec, exec, s[48:49]
	v_lshl_add_u64 v[70:71], s[60:61], 0, v[26:27]
	v_mov_b64_e32 v[72:73], 0xc200000
	v_mov_b64_e32 v[74:75], 0x8200000
	s_or_b64 exec, exec, s[48:49]
	s_waitcnt lgkmcnt(3)
	v_add_f32_e32 v65, v65, v83
	s_waitcnt lgkmcnt(2)
	v_add_f32_e32 v86, v82, v84
	v_lshl_add_u64 v[74:75], s[52:53], 0, v[74:75]
	v_lshlrev_b64 v[82:83], 10, v[70:71]
	v_fmamk_f32 v65, v65, 0x3b800000, v214
	s_mov_b32 s6, 0xf800000
	v_lshl_add_u64 v[74:75], v[74:75], 0, v[82:83]
	v_cmp_gt_f32_e32 vcc, s6, v65
	v_mul_f32_e32 v82, 0x4f800000, v65
	s_nop 0
	v_cndmask_b32_e32 v65, v65, v82, vcc
	v_sqrt_f32_e32 v82, v65
	s_nop 0
	v_add_u32_e32 v83, -1, v82
	v_fma_f32 v84, -v83, v82, v65
	v_cmp_ge_f32_e64 s[48:49], 0, v84
	v_add_u32_e32 v84, 1, v82
	s_nop 0
	v_cndmask_b32_e64 v83, v82, v83, s[48:49]
	v_fma_f32 v82, -v84, v82, v65
	v_cmp_lt_f32_e64 s[48:49], 0, v82
	s_nop 1
	v_cndmask_b32_e64 v82, v83, v84, s[48:49]
	v_mul_f32_e32 v83, 0x37800000, v82
	v_cndmask_b32_e32 v82, v82, v83, vcc
	v_cmp_class_f32_e32 vcc, v65, v215
	s_nop 1
	v_cndmask_b32_e32 v65, v82, v65, vcc
	v_div_scale_f32 v82, s[4:5], v65, v65, 1.0
	v_rcp_f32_e32 v83, v82
	s_nop 0
	v_fma_f32 v84, -v82, v83, 1.0
	v_fmac_f32_e32 v83, v84, v83
	v_div_scale_f32 v84, vcc, 1.0, v65, 1.0
	v_mul_f32_e32 v85, v84, v83
	v_fma_f32 v87, -v82, v85, v84
	v_fmac_f32_e32 v85, v87, v83
	v_fma_f32 v82, -v82, v85, v84
	v_div_fmas_f32 v82, v82, v83, v85
	v_div_fixup_f32 v82, v82, v65, 1.0
	v_pk_mul_f32 v[84:85], v[22:23], v[82:83] op_sel_hi:[1,0]
	v_pk_mul_f32 v[82:83], v[24:25], v[82:83] op_sel_hi:[1,0]
	v_mov_b32_e32 v65, v0
	v_lshl_add_u64 v[74:75], v[74:75], 0, v[64:65]
	v_pk_mul_f32 v[24:25], v[82:83], v[102:103]
	v_pk_mul_f32 v[22:23], v[84:85], v[100:101]
	global_store_dwordx4 v[74:75], v[22:25], off
	s_nop 1
	v_cvt_pk_bf16_f32 v22, v22, v23
	v_cvt_pk_bf16_f32 v23, v24, v25
	v_lshlrev_b64 v[24:25], 9, v[68:69]
	v_lshl_add_u64 v[24:25], v[34:35], 0, v[24:25]
	global_store_dwordx2 v[24:25], v[22:23], off
	v_fmamk_f32 v22, v86, 0x3b2aaaab, v214
	v_cmp_gt_f32_e32 vcc, s6, v22
	v_mul_f32_e32 v23, 0x4f800000, v22
	s_nop 0
	v_cndmask_b32_e32 v22, v22, v23, vcc
	v_sqrt_f32_e32 v23, v22
	s_nop 0
	v_add_u32_e32 v24, -1, v23
	v_fma_f32 v25, -v24, v23, v22
	v_cmp_ge_f32_e64 s[48:49], 0, v25
	v_add_u32_e32 v25, 1, v23
	s_nop 0
	v_cndmask_b32_e64 v24, v23, v24, s[48:49]
	v_fma_f32 v23, -v25, v23, v22
	v_cmp_lt_f32_e64 s[48:49], 0, v23
	s_nop 1
	v_cndmask_b32_e64 v23, v24, v25, s[48:49]
	v_mul_f32_e32 v24, 0x37800000, v23
	v_cndmask_b32_e32 v23, v23, v24, vcc
	v_cmp_class_f32_e32 vcc, v22, v215
	s_nop 1
	v_cndmask_b32_e32 v22, v23, v22, vcc
	v_div_scale_f32 v23, s[4:5], v22, v22, 1.0
	v_rcp_f32_e32 v24, v23
	s_nop 0
	v_fma_f32 v25, -v23, v24, 1.0
	v_fmac_f32_e32 v24, v25, v24
	v_div_scale_f32 v25, vcc, 1.0, v22, 1.0
	v_mul_f32_e32 v65, v25, v24
	v_fma_f32 v74, -v23, v65, v25
	v_fmac_f32_e32 v65, v74, v24
	v_fma_f32 v23, -v23, v65, v25
	v_div_fmas_f32 v23, v23, v24, v65
	v_div_fixup_f32 v22, v23, v22, 1.0
	v_pk_mul_f32 v[24:25], v[18:19], v[22:23] op_sel_hi:[1,0]
	v_pk_mul_f32 v[74:75], v[20:21], v[22:23] op_sel_hi:[1,0]
	v_pk_mul_f32 v[18:19], v[24:25], v[104:105]
	v_pk_mul_f32 v[20:21], v[74:75], v[106:107]
	v_cvt_pk_bf16_f32 v24, v18, v19
	v_lshl_add_u64 v[18:19], s[54:55], 0, v[46:47]
	v_cvt_pk_bf16_f32 v25, v20, v21
	v_add_co_u32_e32 v20, vcc, 0x18600000, v18
	s_nop 1
	v_addc_co_u32_e32 v21, vcc, 0, v19, vcc
	global_store_dwordx2 v[20:21], v[24:25], off
	s_and_saveexec_b64 s[48:49], s[40:41]
	s_cbranch_execz .LBB0_557
; DI unsigned cvtpk(float lo, float hi) { f32x2_t v = {lo, hi}; bf16x2_t b = __builtin_convertvector(v, bf16x2_t); return __builtin_bit_cast(unsigned, b); }
; __global__ void __launch_bounds__(NTHR, 2) mega_fwd(Params P) {
;     ...
;                         const float rs = 1.f / sqrtf(sq[k] * (1.f / 384.f) + EPS);
;                         const f32x4 o0 = vq0[k] * rs * ((const f32x4*)gq)[lane];
;                         u32x2 w; w.x = cvtpk(o0.x, o0.y); w.y = cvtpk(o0.z, o0.w); ((u32x2*)(CQ + (size_t)m * 384))[lane] = w;
;                         if (lane < 32) { const f32x4 o1 = vq1[k] * rs * ((const f32x4*)(gq + 256))[lane]; u32x2 w1; w1.x = cvtpk(o1.x, o1.y); w1.y = cvtpk(o1.z, o1.w); ((u32x2*)(CQ + (size_t)m * 384 + 256))[lane] = w1; }
	v_mov_b32_e32 v23, v22
	v_mov_b32_e32 v20, v22
	v_mov_b32_e32 v21, v22
	v_pk_mul_f32 v[20:21], v[16:17], v[20:21]
	v_pk_mul_f32 v[22:23], v[14:15], v[22:23]
	v_pk_mul_f32 v[16:17], v[20:21], v[110:111]
	v_pk_mul_f32 v[14:15], v[22:23], v[108:109]
	s_nop 0
	v_cvt_pk_bf16_f32 v14, v14, v15
	v_cvt_pk_bf16_f32 v15, v16, v17
	v_add_co_u32_e32 v16, vcc, 0x18600000, v18
	s_nop 1
	v_addc_co_u32_e32 v17, vcc, 0, v19, vcc
	global_store_dwordx2 v[16:17], v[14:15], off offset:512
	s_or_b64 exec, exec, s[48:49]
	s_and_saveexec_b64 s[4:5], s[42:43]
	s_xor_b64 s[48:49], exec, s[4:5]
	s_cbranch_execnz .LBB0_558

; DI unsigned cvtpk(float lo, float hi) { f32x2_t v = {lo, hi}; bf16x2_t b = __builtin_convertvector(v, bf16x2_t); return __builtin_bit_cast(unsigned, b); }
; __global__ void __launch_bounds__(NTHR, 2) mega_fwd(Params P) {
;     ...
;                 for (int k = 0; k < 2; ++k) {
;                     if (k == 1 && !has1) break;
;                     const int m = mm[k]; const int pos = pos_of_row(m); const size_t kvr = (size_t)kvrow_of_row(m);
;                     float* ockv; float* okr;
;                     if (m < MP) { ockv = outp + O_CKVP + ((size_t)ll * MP + m) * 256; okr = outp + O_KRP + ((size_t)ll * MP + m) * 32; }
;                     else { ockv = outp + O_CKVS + ((size_t)ll * MS + (m - MP)) * 256; okr = outp + O_KRS + ((size_t)ll * MS + (m - MP)) * 32; }
;                     {
;                         const float rs = 1.f / sqrtf(sk[k] * (1.f / 256.f) + EPS);
;                         const f32x4 o = vk[k] * rs * ((const f32x4*)gkv)[lane];
;                         ((f32x4*)ockv)[lane] = o;
;                         u32x2 w; w.x = cvtpk(o.x, o.y); w.y = cvtpk(o.z, o.w); ((u32x2*)(CKVB + kvr * 256))[lane] = w;
;                     }
;                     {
;                         const float rs = 1.f / sqrtf(sq[k] * (1.f / 384.f) + EPS);
;                         const f32x4 o0 = vq0[k] * rs * ((const f32x4*)gq)[lane];
;                         u32x2 w; w.x = cvtpk(o0.x, o0.y); w.y = cvtpk(o0.z, o0.w); ((u32x2*)(CQ + (size_t)m * 384))[lane] = w;
;                         if (lane < 32) { const f32x4 o1 = vq1[k] * rs * ((const f32x4*)(gq + 256))[lane]; u32x2 w1; w1.x = cvtpk(o1.x, o1.y); w1.y = cvtpk(o1.z, o1.w); ((u32x2*)(CQ + (size_t)m * 384 + 256))[lane] = w1; }
;                     }
.LBB0_562:
	v_ashrrev_i32_e32 v59, 31, v58
	s_mov_b32 s4, 0x8000
	v_cmp_gt_i32_e64 s[44:45], s4, v56
	v_cmp_lt_i32_e32 vcc, s9, v56
	v_and_b32_e32 v22, 63, v56
	v_add_u32_e32 v18, 0xffff8000, v56
	v_mov_b64_e32 v[14:15], v[58:59]
	s_and_saveexec_b64 s[46:47], vcc
	v_lshrrev_b32_e32 v14, 6, v18
	s_movk_i32 s4, 0x1040
	v_mul_lo_u32 v14, v14, s4
	v_or_b32_e32 v14, v14, v22
	v_add_u32_e32 v14, 0x9000, v14
	v_mov_b32_e32 v15, v0
	s_or_b64 exec, exec, s[46:47]
	s_and_saveexec_b64 s[4:5], vcc
	s_xor_b64 s[46:47], exec, s[4:5]
	v_mov_b32_e32 v19, v0
	v_lshl_add_u64 v[16:17], s[58:59], 0, v[18:19]
	s_or_saveexec_b64 s[46:47], s[46:47]
	v_mov_b64_e32 v[18:19], 0xd000000
	v_mov_b64_e32 v[20:21], 0xcf00000
	s_xor_b64 exec, exec, s[46:47]
	v_lshl_add_u64 v[16:17], s[60:61], 0, v[58:59]
	v_mov_b64_e32 v[18:19], 0xc200000
	v_mov_b64_e32 v[20:21], 0x8200000
	s_or_b64 exec, exec, s[46:47]
	s_waitcnt lgkmcnt(1)
	v_add_f32_e32 v23, v33, v67
	v_lshl_add_u64 v[20:21], s[52:53], 0, v[20:21]
	v_lshlrev_b64 v[24:25], 10, v[16:17]
	v_fmamk_f32 v23, v23, 0x3b800000, v214
	v_lshl_add_u64 v[20:21], v[20:21], 0, v[24:25]
	v_cmp_gt_f32_e32 vcc, s6, v23
	v_mul_f32_e32 v24, 0x4f800000, v23
	s_waitcnt lgkmcnt(0)
	v_add_f32_e32 v33, v57, v81
	v_cndmask_b32_e32 v23, v23, v24, vcc
	v_sqrt_f32_e32 v24, v23
	v_mov_b32_e32 v65, v0
	v_lshl_add_u64 v[20:21], v[20:21], 0, v[64:65]
	v_add_u32_e32 v25, -1, v24
	v_fma_f32 v57, -v25, v24, v23
	v_cmp_ge_f32_e64 s[46:47], 0, v57
	v_add_u32_e32 v57, 1, v24
	s_nop 0
	v_cndmask_b32_e64 v25, v24, v25, s[46:47]
	v_fma_f32 v24, -v57, v24, v23
	v_cmp_lt_f32_e64 s[46:47], 0, v24
	s_nop 1
	v_cndmask_b32_e64 v24, v25, v57, s[46:47]
	v_mul_f32_e32 v25, 0x37800000, v24
	v_cndmask_b32_e32 v24, v24, v25, vcc
	v_cmp_class_f32_e32 vcc, v23, v215
	s_nop 1
	v_cndmask_b32_e32 v23, v24, v23, vcc
	v_div_scale_f32 v24, s[4:5], v23, v23, 1.0
	v_rcp_f32_e32 v25, v24
	s_nop 0
	v_fma_f32 v57, -v24, v25, 1.0
	v_fmac_f32_e32 v25, v57, v25
	v_div_scale_f32 v57, vcc, 1.0, v23, 1.0
	v_mul_f32_e32 v60, v57, v25
	v_fma_f32 v62, -v24, v60, v57
	v_fmac_f32_e32 v60, v62, v25
	v_fma_f32 v24, -v24, v60, v57
	v_div_fmas_f32 v24, v24, v25, v60
	v_div_fixup_f32 v24, v24, v23, 1.0
	v_pk_mul_f32 v[66:67], v[10:11], v[24:25] op_sel_hi:[1,0]
	v_pk_mul_f32 v[24:25], v[12:13], v[24:25] op_sel_hi:[1,0]
	v_pk_mul_f32 v[12:13], v[24:25], v[102:103]
	v_pk_mul_f32 v[10:11], v[66:67], v[100:101]
	global_store_dwordx4 v[20:21], v[10:13], off
	s_nop 1
	v_cvt_pk_bf16_f32 v10, v10, v11
	v_cvt_pk_bf16_f32 v11, v12, v13
	v_lshlrev_b64 v[12:13], 9, v[14:15]
	v_lshl_add_u64 v[12:13], v[34:35], 0, v[12:13]
	global_store_dwordx2 v[12:13], v[10:11], off
	v_fmamk_f32 v10, v33, 0x3b2aaaab, v214
	v_cmp_gt_f32_e32 vcc, s6, v10
	v_mul_f32_e32 v11, 0x4f800000, v10
	s_nop 0
	v_cndmask_b32_e32 v10, v10, v11, vcc
	v_sqrt_f32_e32 v11, v10
	s_nop 0
	v_add_u32_e32 v12, -1, v11
	v_fma_f32 v13, -v12, v11, v10
	v_cmp_ge_f32_e64 s[46:47], 0, v13
	v_add_u32_e32 v13, 1, v11
	s_nop 0
	v_cndmask_b32_e64 v12, v11, v12, s[46:47]
	v_fma_f32 v11, -v13, v11, v10
	v_cmp_lt_f32_e64 s[46:47], 0, v11
	s_nop 1
	v_cndmask_b32_e64 v11, v12, v13, s[46:47]
	v_mul_f32_e32 v12, 0x37800000, v11
	v_cndmask_b32_e32 v11, v11, v12, vcc
	v_cmp_class_f32_e32 vcc, v10, v215
	s_nop 1
	v_cndmask_b32_e32 v10, v11, v10, vcc
	v_div_scale_f32 v11, s[4:5], v10, v10, 1.0
	v_rcp_f32_e32 v12, v11
	s_movk_i32 s4, 0x300
	v_fma_f32 v13, -v11, v12, 1.0
	v_fmac_f32_e32 v12, v13, v12
	v_div_scale_f32 v13, vcc, 1.0, v10, 1.0
	v_mul_f32_e32 v20, v13, v12
	v_fma_f32 v21, -v11, v20, v13
	v_fmac_f32_e32 v20, v21, v12
	v_fma_f32 v11, -v11, v20, v13
	v_div_fmas_f32 v11, v11, v12, v20
	v_div_fixup_f32 v10, v11, v10, 1.0
	v_pk_mul_f32 v[6:7], v[6:7], v[10:11] op_sel_hi:[1,0]
	v_pk_mul_f32 v[8:9], v[8:9], v[10:11] op_sel_hi:[1,0]
	v_pk_mul_f32 v[6:7], v[6:7], v[104:105]
	v_pk_mul_f32 v[8:9], v[8:9], v[106:107]
	v_cvt_pk_bf16_f32 v12, v6, v7
	v_cvt_pk_bf16_f32 v13, v8, v9
	v_mad_i64_i32 v[6:7], s[4:5], v58, s4, v[44:45]
	global_store_dwordx2 v[6:7], v[12:13], off
	s_and_saveexec_b64 s[46:47], s[40:41]
	s_cbranch_execz .LBB0_571
	v_mov_b32_e32 v11, v10
	v_mov_b32_e32 v8, v10
	v_mov_b32_e32 v9, v10
	v_pk_mul_f32 v[8:9], v[4:5], v[8:9]
	v_pk_mul_f32 v[10:11], v[2:3], v[10:11]
	v_pk_mul_f32 v[4:5], v[8:9], v[110:111]
	v_pk_mul_f32 v[2:3], v[10:11], v[108:109]
	s_nop 0
	v_cvt_pk_bf16_f32 v2, v2, v3
	v_cvt_pk_bf16_f32 v3, v4, v5
	global_store_dwordx2 v[6:7], v[2:3], off offset:512
	s_or_b64 exec, exec, s[46:47]
	s_and_saveexec_b64 s[4:5], s[42:43]
	s_xor_b64 s[46:47], exec, s[4:5]
	s_cbranch_execnz .LBB0_572
